# attention: bias table built once per workgroup; lambda/norm-weight prologue loads batched
# baseline (speedup 1.0000x reference)
; DI void attn_mfma_phase(PP P, int l, unsigned char* lds, int G, int cid) {
;     ...
;     for (int i = 0; i < 64; ++i) { d1 += P->in[15][l * 64 + i] * P->in[16][l * 64 + i]; d2 += P->in[17][l * 64 + i] * P->in[18][l * 64 + i];
;         mq = fmaxf(mq, fabsf(P->in[13][l * 64 + i])); mk = fmaxf(mk, fabsf(P->in[14][l * 64 + i])); }
.LBB0_205:
	s_mov_b32 s38, s7
	s_mov_b32 s39, s8
	global_load_dwordx4 v[8:11], v1, s[38:39]
	global_load_dwordx4 v[12:15], v1, s[38:39] offset:16
	global_load_dwordx4 v[16:19], v1, s[38:39] offset:32
	global_load_dwordx4 v[20:23], v1, s[38:39] offset:48
	s_mov_b32 s38, s28
	s_mov_b32 s39, s29
	global_load_dwordx4 v[24:27], v1, s[38:39]
	global_load_dwordx4 v[28:31], v1, s[38:39] offset:16
	global_load_dwordx4 v[32:35], v1, s[38:39] offset:32
	global_load_dwordx4 v[36:39], v1, s[38:39] offset:48
	s_mov_b32 s38, s17
	s_mov_b32 s39, s20
	global_load_dwordx4 v[40:43], v1, s[38:39]
	global_load_dwordx4 v[44:47], v1, s[38:39] offset:16
	global_load_dwordx4 v[48:51], v1, s[38:39] offset:32
	global_load_dwordx4 v[52:55], v1, s[38:39] offset:48
	s_mov_b32 s38, s15
	s_mov_b32 s39, s16
	global_load_dwordx4 v[56:59], v1, s[38:39]
	global_load_dwordx4 v[60:63], v1, s[38:39] offset:16
	global_load_dwordx4 v[64:67], v1, s[38:39] offset:32
	global_load_dwordx4 v[68:71], v1, s[38:39] offset:48
	s_mov_b32 s38, s9
	s_mov_b32 s39, s14
	global_load_dwordx4 v[72:75], v1, s[38:39]
	global_load_dwordx4 v[76:79], v1, s[38:39] offset:16
	global_load_dwordx4 v[80:83], v1, s[38:39] offset:32
	global_load_dwordx4 v[84:87], v1, s[38:39] offset:48
	s_mov_b32 s38, s5
	s_mov_b32 s39, s6
	global_load_dwordx4 v[88:91], v1, s[38:39]
	global_load_dwordx4 v[92:95], v1, s[38:39] offset:16
	global_load_dwordx4 v[96:99], v1, s[38:39] offset:32
	global_load_dwordx4 v[100:103], v1, s[38:39] offset:48
	s_waitcnt vmcnt(0)
	v_fma_f32 v2, v8, v24, v2
	v_fma_f32 v3, v40, v56, v3
	v_fma_f32 v2, v9, v25, v2
	v_fma_f32 v3, v41, v57, v3
	v_fma_f32 v2, v10, v26, v2
	v_fma_f32 v3, v42, v58, v3
	v_fma_f32 v2, v11, v27, v2
	v_fma_f32 v3, v43, v59, v3
	v_max3_f32 v5, v5, |v72|, |v73|
	v_max3_f32 v5, v5, |v74|, |v75|
	v_max3_f32 v0, v0, |v88|, |v89|
	v_max3_f32 v0, v0, |v90|, |v91|
	v_fma_f32 v2, v12, v28, v2
	v_fma_f32 v3, v44, v60, v3
	v_fma_f32 v2, v13, v29, v2
	v_fma_f32 v3, v45, v61, v3
	v_fma_f32 v2, v14, v30, v2
	v_fma_f32 v3, v46, v62, v3
	v_fma_f32 v2, v15, v31, v2
	v_fma_f32 v3, v47, v63, v3
	v_max3_f32 v5, v5, |v76|, |v77|
	v_max3_f32 v5, v5, |v78|, |v79|
	v_max3_f32 v0, v0, |v92|, |v93|
	v_max3_f32 v0, v0, |v94|, |v95|
	v_fma_f32 v2, v16, v32, v2
	v_fma_f32 v3, v48, v64, v3
	v_fma_f32 v2, v17, v33, v2
	v_fma_f32 v3, v49, v65, v3
	v_fma_f32 v2, v18, v34, v2
	v_fma_f32 v3, v50, v66, v3
	v_fma_f32 v2, v19, v35, v2
	v_fma_f32 v3, v51, v67, v3
	v_max3_f32 v5, v5, |v80|, |v81|
	v_max3_f32 v5, v5, |v82|, |v83|
	v_max3_f32 v0, v0, |v96|, |v97|
	v_max3_f32 v0, v0, |v98|, |v99|
	v_fma_f32 v2, v20, v36, v2
	v_fma_f32 v3, v52, v68, v3
	v_fma_f32 v2, v21, v37, v2
	v_fma_f32 v3, v53, v69, v3
	v_fma_f32 v2, v22, v38, v2
	v_fma_f32 v3, v54, v70, v3
	v_fma_f32 v2, v23, v39, v2
	v_fma_f32 v3, v55, v71, v3
	v_max3_f32 v5, v5, |v84|, |v85|
	v_max3_f32 v5, v5, |v86|, |v87|
	v_max3_f32 v0, v0, |v100|, |v101|
	v_max3_f32 v0, v0, |v102|, |v103|
	s_mov_b32 s38, s7
	s_mov_b32 s39, s8
	global_load_dwordx4 v[8:11], v1, s[38:39] offset:64
	global_load_dwordx4 v[12:15], v1, s[38:39] offset:80
	global_load_dwordx4 v[16:19], v1, s[38:39] offset:96
	global_load_dwordx4 v[20:23], v1, s[38:39] offset:112
	s_mov_b32 s38, s28
	s_mov_b32 s39, s29
	global_load_dwordx4 v[24:27], v1, s[38:39] offset:64
	global_load_dwordx4 v[28:31], v1, s[38:39] offset:80
	global_load_dwordx4 v[32:35], v1, s[38:39] offset:96
	global_load_dwordx4 v[36:39], v1, s[38:39] offset:112
	s_mov_b32 s38, s17
	s_mov_b32 s39, s20
	global_load_dwordx4 v[40:43], v1, s[38:39] offset:64
	global_load_dwordx4 v[44:47], v1, s[38:39] offset:80
	global_load_dwordx4 v[48:51], v1, s[38:39] offset:96
	global_load_dwordx4 v[52:55], v1, s[38:39] offset:112
	s_mov_b32 s38, s15
	s_mov_b32 s39, s16
	global_load_dwordx4 v[56:59], v1, s[38:39] offset:64
	global_load_dwordx4 v[60:63], v1, s[38:39] offset:80
	global_load_dwordx4 v[64:67], v1, s[38:39] offset:96
	global_load_dwordx4 v[68:71], v1, s[38:39] offset:112
	s_mov_b32 s38, s9
	s_mov_b32 s39, s14
	global_load_dwordx4 v[72:75], v1, s[38:39] offset:64
	global_load_dwordx4 v[76:79], v1, s[38:39] offset:80
	global_load_dwordx4 v[80:83], v1, s[38:39] offset:96
	global_load_dwordx4 v[84:87], v1, s[38:39] offset:112
	s_mov_b32 s38, s5
	s_mov_b32 s39, s6
	global_load_dwordx4 v[88:91], v1, s[38:39] offset:64
	global_load_dwordx4 v[92:95], v1, s[38:39] offset:80
	global_load_dwordx4 v[96:99], v1, s[38:39] offset:96
	global_load_dwordx4 v[100:103], v1, s[38:39] offset:112
	s_waitcnt vmcnt(0)
; DI void attn_mfma_phase(PP P, int l, unsigned char* lds, int G, int cid) {
;     ...
;     for (int i = 0; i < 64; ++i) { d1 += P->in[15][l * 64 + i] * P->in[16][l * 64 + i]; d2 += P->in[17][l * 64 + i] * P->in[18][l * 64 + i];
;         mq = fmaxf(mq, fabsf(P->in[13][l * 64 + i])); mk = fmaxf(mk, fabsf(P->in[14][l * 64 + i])); }
	v_fma_f32 v2, v8, v24, v2
	v_fma_f32 v3, v40, v56, v3
	v_fma_f32 v2, v9, v25, v2
	v_fma_f32 v3, v41, v57, v3
	v_fma_f32 v2, v10, v26, v2
	v_fma_f32 v3, v42, v58, v3
	v_fma_f32 v2, v11, v27, v2
	v_fma_f32 v3, v43, v59, v3
	v_max3_f32 v5, v5, |v72|, |v73|
	v_max3_f32 v5, v5, |v74|, |v75|
	v_max3_f32 v0, v0, |v88|, |v89|
	v_max3_f32 v0, v0, |v90|, |v91|
	v_fma_f32 v2, v12, v28, v2
	v_fma_f32 v3, v44, v60, v3
	v_fma_f32 v2, v13, v29, v2
	v_fma_f32 v3, v45, v61, v3
	v_fma_f32 v2, v14, v30, v2
	v_fma_f32 v3, v46, v62, v3
	v_fma_f32 v2, v15, v31, v2
	v_fma_f32 v3, v47, v63, v3
	v_max3_f32 v5, v5, |v76|, |v77|
	v_max3_f32 v5, v5, |v78|, |v79|
	v_max3_f32 v0, v0, |v92|, |v93|
	v_max3_f32 v0, v0, |v94|, |v95|
	v_fma_f32 v2, v16, v32, v2
	v_fma_f32 v3, v48, v64, v3
	v_fma_f32 v2, v17, v33, v2
	v_fma_f32 v3, v49, v65, v3
	v_fma_f32 v2, v18, v34, v2
	v_fma_f32 v3, v50, v66, v3
	v_fma_f32 v2, v19, v35, v2
	v_fma_f32 v3, v51, v67, v3
	v_max3_f32 v5, v5, |v80|, |v81|
	v_max3_f32 v5, v5, |v82|, |v83|
	v_max3_f32 v0, v0, |v96|, |v97|
	v_max3_f32 v0, v0, |v98|, |v99|
	v_fma_f32 v2, v20, v36, v2
	v_fma_f32 v3, v52, v68, v3
	v_fma_f32 v2, v21, v37, v2
	v_fma_f32 v3, v53, v69, v3
	v_fma_f32 v2, v22, v38, v2
	v_fma_f32 v3, v54, v70, v3
	v_fma_f32 v2, v23, v39, v2
	v_fma_f32 v3, v55, v71, v3
	v_max3_f32 v5, v5, |v84|, |v85|
	v_max3_f32 v5, v5, |v86|, |v87|
	v_max3_f32 v0, v0, |v100|, |v101|
	v_max3_f32 v0, v0, |v102|, |v103|
	s_mov_b32 s38, s7
	s_mov_b32 s39, s8
	global_load_dwordx4 v[8:11], v1, s[38:39] offset:128
	global_load_dwordx4 v[12:15], v1, s[38:39] offset:144
	global_load_dwordx4 v[16:19], v1, s[38:39] offset:160
	global_load_dwordx4 v[20:23], v1, s[38:39] offset:176
	s_mov_b32 s38, s28
	s_mov_b32 s39, s29
	global_load_dwordx4 v[24:27], v1, s[38:39] offset:128
	global_load_dwordx4 v[28:31], v1, s[38:39] offset:144
	global_load_dwordx4 v[32:35], v1, s[38:39] offset:160
	global_load_dwordx4 v[36:39], v1, s[38:39] offset:176
	s_mov_b32 s38, s17
	s_mov_b32 s39, s20
	global_load_dwordx4 v[40:43], v1, s[38:39] offset:128
	global_load_dwordx4 v[44:47], v1, s[38:39] offset:144
	global_load_dwordx4 v[48:51], v1, s[38:39] offset:160
	global_load_dwordx4 v[52:55], v1, s[38:39] offset:176
	s_mov_b32 s38, s15
	s_mov_b32 s39, s16
	global_load_dwordx4 v[56:59], v1, s[38:39] offset:128
	global_load_dwordx4 v[60:63], v1, s[38:39] offset:144
	global_load_dwordx4 v[64:67], v1, s[38:39] offset:160
	global_load_dwordx4 v[68:71], v1, s[38:39] offset:176
	s_mov_b32 s38, s9
	s_mov_b32 s39, s14
	global_load_dwordx4 v[72:75], v1, s[38:39] offset:128
	global_load_dwordx4 v[76:79], v1, s[38:39] offset:144
	global_load_dwordx4 v[80:83], v1, s[38:39] offset:160
	global_load_dwordx4 v[84:87], v1, s[38:39] offset:176
	s_mov_b32 s38, s5
	s_mov_b32 s39, s6
	global_load_dwordx4 v[88:91], v1, s[38:39] offset:128
	global_load_dwordx4 v[92:95], v1, s[38:39] offset:144
	global_load_dwordx4 v[96:99], v1, s[38:39] offset:160
	global_load_dwordx4 v[100:103], v1, s[38:39] offset:176
	s_waitcnt vmcnt(0)
	v_fma_f32 v2, v8, v24, v2
	v_fma_f32 v3, v40, v56, v3
	v_fma_f32 v2, v9, v25, v2
	v_fma_f32 v3, v41, v57, v3
	v_fma_f32 v2, v10, v26, v2
	v_fma_f32 v3, v42, v58, v3
	v_fma_f32 v2, v11, v27, v2
	v_fma_f32 v3, v43, v59, v3
	v_max3_f32 v5, v5, |v72|, |v73|
	v_max3_f32 v5, v5, |v74|, |v75|
	v_max3_f32 v0, v0, |v88|, |v89|
	v_max3_f32 v0, v0, |v90|, |v91|
	v_fma_f32 v2, v12, v28, v2
	v_fma_f32 v3, v44, v60, v3
	v_fma_f32 v2, v13, v29, v2
	v_fma_f32 v3, v45, v61, v3
	v_fma_f32 v2, v14, v30, v2
	v_fma_f32 v3, v46, v62, v3
	v_fma_f32 v2, v15, v31, v2
	v_fma_f32 v3, v47, v63, v3
	v_max3_f32 v5, v5, |v76|, |v77|
	v_max3_f32 v5, v5, |v78|, |v79|
	v_max3_f32 v0, v0, |v92|, |v93|
	v_max3_f32 v0, v0, |v94|, |v95|
	v_fma_f32 v2, v16, v32, v2
	v_fma_f32 v3, v48, v64, v3
	v_fma_f32 v2, v17, v33, v2
	v_fma_f32 v3, v49, v65, v3
	v_fma_f32 v2, v18, v34, v2
	v_fma_f32 v3, v50, v66, v3
	v_fma_f32 v2, v19, v35, v2
	v_fma_f32 v3, v51, v67, v3
	v_max3_f32 v5, v5, |v80|, |v81|
	v_max3_f32 v5, v5, |v82|, |v83|
	v_max3_f32 v0, v0, |v96|, |v97|
	v_max3_f32 v0, v0, |v98|, |v99|
	v_fma_f32 v2, v20, v36, v2
	v_fma_f32 v3, v52, v68, v3
	v_fma_f32 v2, v21, v37, v2
	v_fma_f32 v3, v53, v69, v3
	v_fma_f32 v2, v22, v38, v2
	v_fma_f32 v3, v54, v70, v3
	v_fma_f32 v2, v23, v39, v2
	v_fma_f32 v3, v55, v71, v3
	v_max3_f32 v5, v5, |v84|, |v85|
	v_max3_f32 v5, v5, |v86|, |v87|
	v_max3_f32 v0, v0, |v100|, |v101|
	v_max3_f32 v0, v0, |v102|, |v103|
	s_mov_b32 s38, s7
	s_mov_b32 s39, s8
	global_load_dwordx4 v[8:11], v1, s[38:39] offset:192
	global_load_dwordx4 v[12:15], v1, s[38:39] offset:208
	global_load_dwordx4 v[16:19], v1, s[38:39] offset:224
	global_load_dwordx4 v[20:23], v1, s[38:39] offset:240
	s_mov_b32 s38, s28
	s_mov_b32 s39, s29
	global_load_dwordx4 v[24:27], v1, s[38:39] offset:192
	global_load_dwordx4 v[28:31], v1, s[38:39] offset:208
	global_load_dwordx4 v[32:35], v1, s[38:39] offset:224
	global_load_dwordx4 v[36:39], v1, s[38:39] offset:240
	s_mov_b32 s38, s17
	s_mov_b32 s39, s20
	global_load_dwordx4 v[40:43], v1, s[38:39] offset:192
	global_load_dwordx4 v[44:47], v1, s[38:39] offset:208
	global_load_dwordx4 v[48:51], v1, s[38:39] offset:224
	global_load_dwordx4 v[52:55], v1, s[38:39] offset:240
	s_mov_b32 s38, s15
	s_mov_b32 s39, s16
	global_load_dwordx4 v[56:59], v1, s[38:39] offset:192
	global_load_dwordx4 v[60:63], v1, s[38:39] offset:208
	global_load_dwordx4 v[64:67], v1, s[38:39] offset:224
	global_load_dwordx4 v[68:71], v1, s[38:39] offset:240
	s_mov_b32 s38, s9
	s_mov_b32 s39, s14
	global_load_dwordx4 v[72:75], v1, s[38:39] offset:192
	global_load_dwordx4 v[76:79], v1, s[38:39] offset:208
	global_load_dwordx4 v[80:83], v1, s[38:39] offset:224
	global_load_dwordx4 v[84:87], v1, s[38:39] offset:240
	s_mov_b32 s38, s5
	s_mov_b32 s39, s6
	global_load_dwordx4 v[88:91], v1, s[38:39] offset:192
	global_load_dwordx4 v[92:95], v1, s[38:39] offset:208
	global_load_dwordx4 v[96:99], v1, s[38:39] offset:224
	global_load_dwordx4 v[100:103], v1, s[38:39] offset:240
	s_waitcnt vmcnt(0)
; DI void attn_mfma_phase(PP P, int l, unsigned char* lds, int G, int cid) {
;     ...
;     for (int i = 0; i < 64; ++i) { d1 += P->in[15][l * 64 + i] * P->in[16][l * 64 + i]; d2 += P->in[17][l * 64 + i] * P->in[18][l * 64 + i];
;         mq = fmaxf(mq, fabsf(P->in[13][l * 64 + i])); mk = fmaxf(mk, fabsf(P->in[14][l * 64 + i])); }
;     ...
;     for (int u = cid; u < 1024; u += G) {
	v_fma_f32 v2, v8, v24, v2
	v_fma_f32 v3, v40, v56, v3
	v_fma_f32 v2, v9, v25, v2
	v_fma_f32 v3, v41, v57, v3
	v_fma_f32 v2, v10, v26, v2
	v_fma_f32 v3, v42, v58, v3
	v_fma_f32 v2, v11, v27, v2
	v_fma_f32 v3, v43, v59, v3
	v_max3_f32 v5, v5, |v72|, |v73|
	v_max3_f32 v5, v5, |v74|, |v75|
	v_max3_f32 v0, v0, |v88|, |v89|
	v_max3_f32 v0, v0, |v90|, |v91|
	v_fma_f32 v2, v12, v28, v2
	v_fma_f32 v3, v44, v60, v3
	v_fma_f32 v2, v13, v29, v2
	v_fma_f32 v3, v45, v61, v3
	v_fma_f32 v2, v14, v30, v2
	v_fma_f32 v3, v46, v62, v3
	v_fma_f32 v2, v15, v31, v2
	v_fma_f32 v3, v47, v63, v3
	v_max3_f32 v5, v5, |v76|, |v77|
	v_max3_f32 v5, v5, |v78|, |v79|
	v_max3_f32 v0, v0, |v92|, |v93|
	v_max3_f32 v0, v0, |v94|, |v95|
	v_fma_f32 v2, v16, v32, v2
	v_fma_f32 v3, v48, v64, v3
	v_fma_f32 v2, v17, v33, v2
	v_fma_f32 v3, v49, v65, v3
	v_fma_f32 v2, v18, v34, v2
	v_fma_f32 v3, v50, v66, v3
	v_fma_f32 v2, v19, v35, v2
	v_fma_f32 v3, v51, v67, v3
	v_max3_f32 v5, v5, |v80|, |v81|
	v_max3_f32 v5, v5, |v82|, |v83|
	v_max3_f32 v0, v0, |v96|, |v97|
	v_max3_f32 v0, v0, |v98|, |v99|
	v_fma_f32 v2, v20, v36, v2
	v_fma_f32 v3, v52, v68, v3
	v_fma_f32 v2, v21, v37, v2
	v_fma_f32 v3, v53, v69, v3
	v_fma_f32 v2, v22, v38, v2
	v_fma_f32 v3, v54, v70, v3
	v_fma_f32 v2, v23, v39, v2
	v_fma_f32 v3, v55, v71, v3
	v_max3_f32 v5, v5, |v84|, |v85|
	v_max3_f32 v5, v5, |v86|, |v87|
	v_max3_f32 v0, v0, |v100|, |v101|
	v_max3_f32 v0, v0, |v102|, |v103|
	s_cmpk_lt_i32 s79, 0x400
	s_cbranch_scc0 .LBB0_227
; DI void attn_mfma_phase(PP P, int l, unsigned char* lds, int G, int cid) {
;     ...
;     const float linit = (l == 0) ? 0.2f : 0.35550906759096926f;
;     float d1 = 0.f, d2 = 0.f, mq = 0.f, mk = 0.f;
;     for (int i = 0; i < 64; ++i) { d1 += P->in[15][l * 64 + i] * P->in[16][l * 64 + i]; d2 += P->in[17][l * 64 + i] * P->in[18][l * 64 + i];
;         mq = fmaxf(mq, fabsf(P->in[13][l * 64 + i])); mk = fmaxf(mk, fabsf(P->in[14][l * 64 + i])); }
;     const float lam = expf(d1) - expf(d2) + linit;
;     const int pir = (r32 & ~12) | ((r32 & 4) << 1) | ((r32 & 8) >> 1);
;     int kro[4], vro[4];
; #pragma unroll
;     for (int k = 0; k < 4; ++k) { kro[k] = pir * 256 + (((map * 8 + k * 2 + hi) ^ (pir & 15)) * 16); vro[k] = AT_V0 + r32 * 128 + (((k * 2 + hi) ^ ((r32 >> 1) & 7)) * 16); }
;     ...
;         if (tid < 192) tb2[tid] = P->in[23][t5_bucket(tid - 128) * 8 + h] * LOG2E - smax2;
	v_and_b32_e32 v9, 19, v4
	v_lshlrev_b32_e32 v10, 1, v4
	v_and_or_b32 v9, v10, 8, v9
	v_lshrrev_b32_e32 v10, 1, v4
	v_bfe_u32 v8, v4, 5, 1
	s_ashr_i32 s5, s4, 8
	v_and_b32_e32 v11, 4, v10
	v_or_b32_e32 v12, v9, v11
	v_lshl_or_b32 v14, s5, 3, v8
	v_lshlrev_b32_e32 v13, 8, v12
	v_bitop3_b32 v9, v9, 15, v11 bitop3:0xc8
	v_bitop3_b32 v12, v12, v14, 15 bitop3:0x6c
	v_lshl_add_u32 v171, v12, 4, v13
	v_bitop3_b32 v12, v14, v9, 2 bitop3:0x36
	v_bitop3_b32 v16, v14, v9, 4 bitop3:0x36
	v_bitop3_b32 v9, v14, v9, 6 bitop3:0x36
	v_lshl_add_u32 v200, v12, 4, v13
	v_lshl_add_u32 v201, v16, 4, v13
	v_lshl_add_u32 v202, v9, 4, v13
	v_mul_f32_e32 v13, 0x3fb8aa3b, v2
	v_bfe_u32 v15, v4, 1, 3
	v_rndne_f32_e32 v14, v13
	v_bitop3_b32 v12, v8, v15, 2 bitop3:0x36
	v_bitop3_b32 v16, v8, v15, 4 bitop3:0x36
	v_bitop3_b32 v9, v8, v15, 6 bitop3:0x36
	v_sub_f32_e32 v15, v13, v14
	v_fma_f32 v13, v2, s30, -v13
	v_fmac_f32_e32 v13, 0x32a5705f, v2
	v_add_f32_e32 v13, v15, v13
	v_exp_f32_e32 v13, v13
	v_cvt_i32_f32_e32 v14, v14
	s_add_u32 s28, s70, 0xf400000
	s_addc_u32 s29, s71, 0
	s_cmp_lt_u32 s77, 8
	s_cselect_b64 vcc, -1, 0
	v_mov_b32_e32 v15, 0x3eb60549
	v_mov_b32_e32 v17, 0x3e4ccccd
	v_ldexp_f32 v13, v13, v14
	v_mul_f32_e32 v14, 0x3fb8aa3b, v3
	v_cndmask_b32_e32 v15, v15, v17, vcc
	v_rndne_f32_e32 v17, v14
	v_sub_f32_e32 v18, v14, v17
	v_fma_f32 v14, v3, s30, -v14
	v_fmac_f32_e32 v14, 0x32a5705f, v3
	v_add_f32_e32 v14, v18, v14
	v_exp_f32_e32 v14, v14
	v_cvt_i32_f32_e32 v17, v17
	v_cmp_ngt_f32_e32 vcc, s62, v2
	s_mov_b32 s6, 0x3f317217
	s_mov_b32 s10, 0x40317218
	v_cndmask_b32_e32 v13, 0, v13, vcc
	v_cmp_nlt_f32_e32 vcc, s63, v2
	s_ashr_i32 s8, s4, 6
	s_and_b32 s9, s8, 3
	v_cndmask_b32_e32 v2, v211, v13, vcc
	v_ldexp_f32 v13, v14, v17
	v_cmp_ngt_f32_e32 vcc, s62, v3
	s_add_u32 s12, s70, 0x21400000
	s_addc_u32 s13, s71, 0
	v_cndmask_b32_e32 v13, 0, v13, vcc
	v_cmp_nlt_f32_e32 vcc, s63, v3
	v_and_b32_e32 v7, 31, v4
	v_lshlrev_b32_e32 v162, 3, v8
	v_cndmask_b32_e32 v3, v211, v13, vcc
	v_sub_f32_e32 v2, v2, v3
	v_add_u32_e32 v3, 0xffffff80, v4
	v_sub_u32_e32 v13, 0x80, v4
	v_max_i32_e32 v3, v3, v13
	v_cvt_f32_u32_e32 v13, v3
	v_add_f32_e32 v160, v15, v2
	s_lshl_b32 s16, s5, 6
	s_lshl_b32 s64, s8, 11
	v_mul_f32_e32 v2, 0x3e000000, v13
	v_cmp_gt_f32_e32 vcc, s27, v2
	s_bfe_u32 s60, s8, 0x10001
	s_add_i32 s61, 0, 0x20000
	v_cndmask_b32_e64 v13, 0, 32, vcc
	v_ldexp_f32 v2, v2, v13
	v_log_f32_e32 v2, v2
	s_ashr_i32 s17, s16, 31
	s_add_i32 s65, s64, 0
	v_mul_f32_e32 v5, 0x41000000, v5
	v_mul_f32_e32 v13, 0x3f317217, v2
	v_fma_f32 v13, v2, s6, -v13
	v_fmac_f32_e32 v13, 0x3377d1cf, v2
	s_mov_b32 s6, 0x7f800000
	v_fmac_f32_e32 v13, 0x3f317217, v2
	v_cmp_lt_f32_e64 s[40:41], |v2|, s6
	v_mul_f32_e32 v204, v0, v5
	v_bfe_u32 v5, v4, 4, 2
	v_cndmask_b32_e64 v2, v2, v13, s[40:41]
	v_mov_b32_e32 v13, 0x41b17218
	v_cndmask_b32_e32 v13, 0, v13, vcc
	v_sub_f32_e32 v2, v2, v13
	v_div_scale_f32 v13, s[6:7], s10, s10, v2
	v_rcp_f32_e32 v14, v13
	s_lshl_b32 s6, s9, 5
	s_and_b32 s11, s6, 32
	s_movk_i32 s7, 0xc0
	v_fma_f32 v17, -v13, v14, 1.0
	v_fmac_f32_e32 v14, v17, v14
	v_div_scale_f32 v17, vcc, v2, s10, v2
	v_mul_f32_e32 v18, v17, v14
	v_fma_f32 v19, -v13, v18, v17
	v_fmac_f32_e32 v18, v19, v14
	v_fma_f32 v13, -v13, v18, v17
	v_div_fmas_f32 v13, v13, v14, v18
	v_div_fixup_f32 v2, v13, s10, v2
	v_mov_b32_e32 v13, 0x38d1b717
	v_fmamk_f32 v2, v2, 0x41000000, v13
	v_cvt_i32_f32_e32 v2, v2
	v_or_b32_e32 v216, s11, v7
	v_or_b32_e32 v14, 0x80, v162
	v_cmp_gt_i32_e64 s[40:41], s7, v4
	s_movk_i32 s7, 0x80
	s_lshl_b32 s10, s8, 1
	v_sub_u32_e32 v14, v14, v216
	v_and_b32_e32 v17, 64, v215
	v_cmp_lt_i32_e32 vcc, s7, v4
	s_cmp_gt_u32 s9, 1
	v_lshl_add_u32 v217, v14, 2, s61
	v_xor_b32_e32 v14, 32, v215
	v_add_u32_e32 v17, 64, v17
	v_min_i32_e32 v0, 7, v2
	v_cndmask_b32_e64 v2, 0, 16, vcc
	s_cselect_b64 s[44:45], -1, 0
	v_cmp_lt_i32_e32 vcc, v14, v17
	s_cmp_eq_u32 s5, 1
	v_add_u32_e32 v0, 8, v0
	v_cndmask_b32_e32 v14, v215, v14, vcc
	s_cselect_b64 s[48:49], -1, 0
	s_cmpk_lt_u32 s4, 0x100
	v_cmp_gt_u32_e32 vcc, 8, v3
	s_cselect_b64 s[50:51], -1, 0
	s_lshl_b32 s5, s8, 3
	v_cndmask_b32_e32 v0, v0, v3, vcc
	v_bfe_u32 v13, v4, 3, 3
	v_add_lshl_u32 v221, v0, v2, 3
	v_or_b32_e32 v172, s5, v5
	v_bitop3_b32 v0, s5, v4, v5 bitop3:0x36
	s_or_b32 s5, s10, 1
	v_lshl_or_b32 v174, s8, 4, v13
	s_lshl_b32 s8, s5, 2
	v_lshlrev_b32_e32 v0, 3, v0
	v_bitop3_b32 v3, s8, v4, v5 bitop3:0x36
	v_and_b32_e32 v6, 63, v4
	v_and_b32_e32 v2, 0x78, v0
	v_xor_b32_e32 v0, v5, v4
	v_lshlrev_b32_e32 v3, 3, v3
	v_lshl_or_b32 v178, s5, 3, v13
	v_lshl_add_u32 v219, v6, 2, 0
	v_and_b32_e32 v6, 0x78, v3
	v_lshrrev_b32_e32 v3, 1, v178
	v_lshlrev_b32_e32 v0, 4, v0
	v_xor_b32_e32 v3, v3, v4
	v_and_b32_e32 v0, 0x70, v0
	v_lshlrev_b32_e32 v11, 7, v7
	v_bitop3_b32 v10, v8, v10, 7 bitop3:0x78
	v_or_b32_e32 v203, s6, v7
	v_lshlrev_b32_e32 v170, 2, v8
	s_lshl_b32 s6, s68, 7
	s_lshl_b32 s4, s4, 8
	v_lshl_add_u64 v[180:181], s[12:13], 0, v[0:1]
	v_lshlrev_b32_e32 v0, 4, v3
	v_or_b32_e32 v8, 4, v172
	s_ashr_i32 s7, s6, 31
	v_or_b32_e32 v176, s8, v5
	v_lshl_or_b32 v225, v9, 4, v11
	s_and_b32 s5, s4, 0xc000
	s_or_b32 s66, s4, 0x3f00
	v_and_b32_e32 v0, 0x70, v0
	v_ashrrev_i32_e32 v9, 31, v8
	v_lshl_add_u64 v[182:183], s[12:13], 0, v[0:1]
	s_add_u32 s4, s70, 0xf480000
	v_lshlrev_b64 v[8:9], 11, v[8:9]
	v_bitop3_b32 v0, v176, 15, v4 bitop3:0x48
	s_load_dwordx2 s[14:15], s[0:1], 0xb8
	v_ashrrev_i32_e32 v173, 31, v172
	v_add_u32_e32 v227, s5, v219
	s_addc_u32 s5, s71, 0
	v_lshl_or_b32 v8, v0, 4, v8
	v_lshl_add_u64 v[184:185], s[4:5], 0, v[8:9]
	v_lshlrev_b64 v[8:9], 11, v[172:173]
	v_bitop3_b32 v0, v172, 15, v4 bitop3:0x48
	v_lshl_or_b32 v8, v0, 4, v8
	v_sub_u32_e32 v0, v162, v7
	v_lshl_add_u64 v[186:187], s[4:5], 0, v[8:9]
	v_subrev_u32_e32 v0, s11, v0
	s_lshl_b32 s4, s60, 6
	v_lshl_add_u32 v205, v4, 2, s61
	v_lshlrev_b32_e32 v218, 2, v14
	v_sub_f32_e32 v220, 1.0, v15
	v_ashrrev_i32_e32 v175, 31, v174
	v_ashrrev_i32_e32 v177, 31, v176
	v_ashrrev_i32_e32 v179, 31, v178
	v_lshl_or_b32 v222, v10, 4, v11
	v_lshl_or_b32 v223, v12, 4, v11
	v_lshl_or_b32 v224, v16, 4, v11
	v_lshl_add_u32 v226, s9, 14, v219
	v_mov_b32_e32 v161, v160
	s_lshl_b32 s67, s79, 2
	s_lshl_b32 s72, s78, 2
	v_subrev_u32_e32 v228, s4, v0
	v_lshlrev_b32_e32 v188, 1, v2
	v_lshlrev_b32_e32 v190, 1, v6
	s_add_i32 s73, s65, 0x10400
	s_add_i32 s80, s65, 0x4400
	s_add_i32 s81, s65, 0xc400
	s_lshl_b64 s[58:59], s[6:7], 2
	s_mov_b32 s82, s79
	v_add_u32_e32 v222, 0x8000, v222
	v_add_u32_e32 v223, 0x8000, v223
	v_add_u32_e32 v224, 0x8000, v224
	v_add_u32_e32 v225, 0x8000, v225
	s_branch .LBB0_209
.Lattn_keep_table:
	s_barrier
	s_mov_b64 s[12:13], exec
	s_branch .LBB0_211

; DI void attn_mfma_phase(PP P, int l, unsigned char* lds, int G, int cid) {
;     ...
;     for (int u = cid; u < 1024; u += G) {
;         const int w = u & 255, i = u >> 8, bh = (w & 7) * 4 + (w >> 6), r = (w >> 3) & 7, b = bh >> 3, h = bh & 7;
;         const int j = (i >> 1) * 16 + ((i & 1) ? 15 - r : r);
;         const int mychunk = 2 * j + (qg >> 1), qpos = j * 128 + qg * 32 + r32;
;         float mb = 0.f;
;         for (int k = 0; k < 32; ++k) mb = fmaxf(mb, fabsf(P->in[23][k * 8 + h]));
;         const float smax2 = (8.f * mq * mk + mb) * LOG2E;
;         __syncthreads();
;         if (tid < 192) tb2[tid] = P->in[23][t5_bucket(tid - 128) * 8 + h] * LOG2E - smax2;
.LBB0_209:
	s_lshl_b32 s4, s82, 2
	s_and_b32 s8, s4, 28
	s_bfe_u32 s4, s82, 0x20006
	s_or_b32 s7, s8, s4
	s_and_b32 s39, s7, 7
	s_cmp_lg_u32 s82, s79
	s_cbranch_scc1 .Lattn_keep_table
	s_lshl_b32 s4, s39, 2
	v_mov_b32_e32 v24, s4
	s_lshl_b32 s4, s7, 2
	s_or_b32 s5, s4, 0x60
	v_mov_b32_e32 v25, s5
	s_or_b32 s5, s4, 0xe0
	v_mov_b32_e32 v26, s5
	s_or_b32 s5, s4, 0x160
	v_mov_b32_e32 v27, s5
	s_or_b32 s5, s4, 0x1e0
	v_mov_b32_e32 v28, s5
	s_or_b32 s5, s4, 0x260
	v_mov_b32_e32 v33, s5
	s_or_b32 s5, s4, 0x2e0
	v_mov_b32_e32 v34, s5
	s_or_b32 s5, s4, 0x360
	s_or_b32 s4, s4, 0x3e0
	s_waitcnt lgkmcnt(0)
	global_load_dword v0, v24, s[14:15]
	global_load_dword v2, v24, s[14:15] offset:32
	global_load_dword v3, v24, s[14:15] offset:64
	global_load_dword v4, v24, s[14:15] offset:128
	global_load_dword v5, v24, s[14:15] offset:160
	global_load_dword v6, v24, s[14:15] offset:192
	global_load_dword v7, v24, s[14:15] offset:256
	global_load_dword v8, v24, s[14:15] offset:288
	global_load_dword v9, v24, s[14:15] offset:320
	global_load_dword v10, v24, s[14:15] offset:384
	global_load_dword v11, v24, s[14:15] offset:416
	global_load_dword v12, v24, s[14:15] offset:448
	global_load_dword v13, v24, s[14:15] offset:512
	global_load_dword v14, v24, s[14:15] offset:544
	global_load_dword v15, v24, s[14:15] offset:576
	global_load_dword v16, v24, s[14:15] offset:640
	v_mov_b32_e32 v35, s5
	global_load_dword v17, v24, s[14:15] offset:672
	global_load_dword v18, v24, s[14:15] offset:704
	global_load_dword v19, v24, s[14:15] offset:768
	global_load_dword v20, v24, s[14:15] offset:800
	global_load_dword v21, v24, s[14:15] offset:832
	global_load_dword v22, v24, s[14:15] offset:896
	global_load_dword v23, v24, s[14:15] offset:928
	s_nop 0
	global_load_dword v24, v24, s[14:15] offset:960
	v_mov_b32_e32 v36, s4
	global_load_dword v32, v25, s[14:15]
	global_load_dword v31, v26, s[14:15]
	global_load_dword v30, v27, s[14:15]
	global_load_dword v29, v28, s[14:15]
	s_nop 0
	global_load_dword v28, v33, s[14:15]
	global_load_dword v27, v34, s[14:15]
	global_load_dword v26, v35, s[14:15]
	global_load_dword v25, v36, s[14:15]
	s_barrier
	s_and_saveexec_b64 s[12:13], s[40:41]
	s_cbranch_execz .LBB0_211
	v_or_b32_e32 v34, s39, v221
	v_ashrrev_i32_e32 v35, 31, v34
	v_lshl_add_u64 v[34:35], v[34:35], 2, s[14:15]
	global_load_dword v34, v[34:35], off
	s_waitcnt vmcnt(31)
	v_max3_f32 v0, |v0|, 0, |v2|
	s_waitcnt vmcnt(8)
	v_max3_f32 v0, v0, |v3|, |v32|
	v_max3_f32 v0, v0, |v4|, |v5|
	s_waitcnt vmcnt(7)
	v_max3_f32 v0, v0, |v6|, |v31|
	v_max3_f32 v0, v0, |v7|, |v8|
	s_waitcnt vmcnt(6)
	v_max3_f32 v0, v0, |v9|, |v30|
	v_max3_f32 v0, v0, |v10|, |v11|
	s_waitcnt vmcnt(5)
	v_max3_f32 v0, v0, |v12|, |v29|
	v_max3_f32 v0, v0, |v13|, |v14|
	s_waitcnt vmcnt(4)
	v_max3_f32 v0, v0, |v15|, |v28|
	v_max3_f32 v0, v0, |v16|, |v17|
	s_waitcnt vmcnt(3)
	v_max3_f32 v0, v0, |v18|, |v27|
	v_max3_f32 v0, v0, |v19|, |v20|
	s_waitcnt vmcnt(2)
	v_max3_f32 v0, v0, |v21|, |v26|
	v_max3_f32 v0, v0, |v22|, |v23|
	s_waitcnt vmcnt(1)
	v_max3_f32 v0, v0, |v24|, |v25|
	v_add_f32_e32 v35, v204, v0
	s_waitcnt vmcnt(0)
	v_pk_mul_f32 v[2:3], v[34:35], s[30:31] op_sel_hi:[1,0]
	s_nop 0
	v_sub_f32_e32 v0, v2, v3
	ds_write_b32 v205, v0
